# fused lean tile in four copies, stage byte offset as an LDS-read immediate (no per-tile address VALU)
# baseline (speedup 1.0000x reference)
.LBB0_658:
	s_and_b64 vcc, exec, s[0:1]
	s_cbranch_vccz .LBB0_653
	s_lshl_b32 s0, s76, 14
	s_or_b32 s76, s0, s21
	s_lshl_b32 s77, s77, 6
	s_add_i32 s78, s77, 63
	s_cmp_gt_i32 s78, s72
	s_cbranch_scc1 .Lflt_no
	s_cmp_lt_i32 s77, s71
	s_cbranch_scc1 .Lflt_no
	s_sub_i32 s0, s33, s78
	s_cmpk_gt_i32 s0, 0x7f
	s_cselect_b64 s[0:1], -1, 0
	s_or_b64 s[0:1], s[0:1], s[30:31]
	s_and_b64 vcc, exec, s[0:1]
	s_cbranch_vccz .Lflt_no
	s_cmpk_eq_u32 s76, 0
	s_cbranch_scc1 .Lflt_v0
	s_cmpk_eq_u32 s76, 0x4000
	s_cbranch_scc1 .Lflt_v1
	s_cmpk_eq_u32 s76, 0x8000
	s_cbranch_scc1 .Lflt_v2
	ds_read_b128 v[4:7], v198 offset:49152
	ds_read_b128 v[8:11], v206 offset:49152
	ds_read_b128 v[12:15], v207 offset:49152
	ds_read_b128 v[214:217], v208 offset:49152
	ds_read_b128 v[234:237], v198 offset:53248
	ds_read_b128 v[244:247], v206 offset:53248
	ds_read_b128 v[248:251], v207 offset:53248
	ds_read_b128 v[252:255], v208 offset:53248
	s_setprio 1
	s_waitcnt lgkmcnt(7)
	v_mfma_f32_32x32x16_bf16 v[118:133], v[4:7], v[134:137], v[86:101]
	s_waitcnt lgkmcnt(6)
	v_mfma_f32_32x32x16_bf16 v[118:133], v[8:11], v[138:141], v[118:133]
	s_waitcnt lgkmcnt(5)
	v_mfma_f32_32x32x16_bf16 v[118:133], v[12:15], v[142:145], v[118:133]
	s_waitcnt lgkmcnt(4)
	v_mfma_f32_32x32x16_bf16 v[118:133], v[214:217], v[150:153], v[118:133]
	v_mfma_f32_32x32x16_bf16 v[102:117], v[4:7], v[146:149], v[86:101]
	ds_read_b64_tr_b16 v[4:5], v200 offset:57344
	ds_read_b64_tr_b16 v[6:7], v200 offset:58368
	v_mfma_f32_32x32x16_bf16 v[102:117], v[8:11], v[154:157], v[102:117]
	ds_read_b64_tr_b16 v[8:9], v200 offset:59392
	ds_read_b64_tr_b16 v[10:11], v200 offset:60416
	s_nop 5
	v_exp_f32_e32 v118, v118
	v_exp_f32_e32 v119, v119
	v_exp_f32_e32 v120, v120
	v_mfma_f32_32x32x16_bf16 v[102:117], v[12:15], v[158:161], v[102:117]
	ds_read_b64_tr_b16 v[12:13], v201 offset:57344
	ds_read_b64_tr_b16 v[14:15], v201 offset:58368
	v_exp_f32_e32 v121, v121
	v_exp_f32_e32 v122, v122
	v_exp_f32_e32 v123, v123
	v_mfma_f32_32x32x16_bf16 v[102:117], v[214:217], v[162:165], v[102:117]
	ds_read_b64_tr_b16 v[214:215], v201 offset:59392
	ds_read_b64_tr_b16 v[216:217], v201 offset:60416
	v_exp_f32_e32 v124, v124
	v_exp_f32_e32 v125, v125
	v_exp_f32_e32 v126, v126
	s_waitcnt lgkmcnt(8)
	v_mfma_f32_32x32x16_bf16 v[218:233], v[234:237], v[134:137], v[86:101]
	v_exp_f32_e32 v127, v127
	v_exp_f32_e32 v128, v128
	v_exp_f32_e32 v129, v129
	v_mfma_f32_32x32x16_bf16 v[218:233], v[244:247], v[138:141], v[218:233]
	v_exp_f32_e32 v130, v130
	v_exp_f32_e32 v131, v131
	v_exp_f32_e32 v132, v132
	v_mfma_f32_32x32x16_bf16 v[218:233], v[248:251], v[142:145], v[218:233]
	v_exp_f32_e32 v133, v133
	v_add_f32_e32 v16, v118, v120
	v_add_f32_e32 v17, v119, v121
	v_add_f32_e32 v16, v16, v122
	v_add_f32_e32 v17, v17, v123
	v_add_f32_e32 v16, v16, v124
	v_add_f32_e32 v17, v17, v125
	v_cvt_pk_bf16_f32 v118, v118, v119
	v_cvt_pk_bf16_f32 v119, v120, v121
	v_cvt_pk_bf16_f32 v120, v122, v123
	v_mfma_f32_32x32x16_bf16 v[218:233], v[252:255], v[150:153], v[218:233]
	v_cvt_pk_bf16_f32 v121, v124, v125
	v_cvt_pk_bf16_f32 v122, v126, v127
	v_cvt_pk_bf16_f32 v123, v128, v129
	v_cvt_pk_bf16_f32 v124, v130, v131
	v_cvt_pk_bf16_f32 v125, v132, v133
	v_add_f32_e32 v16, v16, v126
	v_add_f32_e32 v17, v17, v127
	v_add_f32_e32 v16, v16, v128
	v_add_f32_e32 v17, v17, v129
	v_add_f32_e32 v16, v16, v130
	v_add_f32_e32 v17, v17, v131
	v_add_f32_e32 v16, v16, v132
	v_add_f32_e32 v17, v17, v133
	s_waitcnt lgkmcnt(0)
	v_mfma_f32_32x32x16_bf16 v[20:35], v[4:7], v[118:121], v[20:35]
	v_exp_f32_e32 v102, v102
	v_exp_f32_e32 v103, v103
	v_exp_f32_e32 v104, v104
	v_mfma_f32_32x32x16_bf16 v[36:51], v[12:15], v[118:121], v[36:51]
	v_exp_f32_e32 v105, v105
	v_exp_f32_e32 v106, v106
	v_exp_f32_e32 v107, v107
	v_mfma_f32_32x32x16_bf16 v[20:35], v[8:11], v[122:125], v[20:35]
	v_exp_f32_e32 v108, v108
	v_exp_f32_e32 v109, v109
	v_exp_f32_e32 v110, v110
	v_mfma_f32_32x32x16_bf16 v[36:51], v[214:217], v[122:125], v[36:51]
	v_exp_f32_e32 v111, v111
	v_exp_f32_e32 v112, v112
	v_exp_f32_e32 v113, v113
	v_mfma_f32_32x32x16_bf16 v[118:133], v[234:237], v[146:149], v[86:101]
	ds_read_b64_tr_b16 v[234:235], v200 offset:61440
	ds_read_b64_tr_b16 v[236:237], v200 offset:62464
	v_exp_f32_e32 v114, v114
	v_exp_f32_e32 v115, v115
	v_exp_f32_e32 v116, v116
	v_mfma_f32_32x32x16_bf16 v[118:133], v[244:247], v[154:157], v[118:133]
	ds_read_b64_tr_b16 v[244:245], v200 offset:63488
	ds_read_b64_tr_b16 v[246:247], v200 offset:64512
	v_exp_f32_e32 v117, v117
	v_add_f32_e32 v238, v102, v104
	v_add_f32_e32 v239, v103, v105
	v_add_f32_e32 v238, v238, v106
	v_add_f32_e32 v239, v239, v107
	v_add_f32_e32 v238, v238, v108
	v_add_f32_e32 v239, v239, v109
	v_cvt_pk_bf16_f32 v102, v102, v103
	v_cvt_pk_bf16_f32 v103, v104, v105
	v_mfma_f32_32x32x16_bf16 v[118:133], v[248:251], v[158:161], v[118:133]
	ds_read_b64_tr_b16 v[248:249], v201 offset:61440
	ds_read_b64_tr_b16 v[250:251], v201 offset:62464
	v_cvt_pk_bf16_f32 v104, v106, v107
	v_cvt_pk_bf16_f32 v105, v108, v109
	v_cvt_pk_bf16_f32 v106, v110, v111
	v_cvt_pk_bf16_f32 v107, v112, v113
	v_cvt_pk_bf16_f32 v108, v114, v115
	v_cvt_pk_bf16_f32 v109, v116, v117
	v_mfma_f32_32x32x16_bf16 v[118:133], v[252:255], v[162:165], v[118:133]
	ds_read_b64_tr_b16 v[252:253], v201 offset:63488
	ds_read_b64_tr_b16 v[254:255], v201 offset:64512
	v_add_f32_e32 v238, v238, v110
	v_add_f32_e32 v239, v239, v111
	v_add_f32_e32 v238, v238, v112
	v_add_f32_e32 v239, v239, v113
	v_add_f32_e32 v238, v238, v114
	v_add_f32_e32 v239, v239, v115
	v_add_f32_e32 v238, v238, v116
	v_add_f32_e32 v239, v239, v117
	v_mfma_f32_32x32x16_bf16 v[68:83], v[4:7], v[102:105], v[68:83]
	v_exp_f32_e32 v218, v218
	v_exp_f32_e32 v219, v219
	v_exp_f32_e32 v220, v220
	v_mfma_f32_32x32x16_bf16 v[52:67], v[12:15], v[102:105], v[52:67]
	v_exp_f32_e32 v221, v221
	v_exp_f32_e32 v222, v222
	v_exp_f32_e32 v223, v223
	v_mfma_f32_32x32x16_bf16 v[68:83], v[8:11], v[106:109], v[68:83]
	v_exp_f32_e32 v224, v224
	v_exp_f32_e32 v225, v225
	v_exp_f32_e32 v226, v226
	v_mfma_f32_32x32x16_bf16 v[52:67], v[214:217], v[106:109], v[52:67]
	v_exp_f32_e32 v227, v227
	v_exp_f32_e32 v228, v228
	v_exp_f32_e32 v229, v229
	v_exp_f32_e32 v230, v230
	v_exp_f32_e32 v231, v231
	v_exp_f32_e32 v232, v232
	v_exp_f32_e32 v233, v233
	v_add_f32_e32 v16, v16, v218
	v_add_f32_e32 v17, v17, v219
	v_add_f32_e32 v16, v16, v220
	v_add_f32_e32 v17, v17, v221
	v_add_f32_e32 v16, v16, v222
	v_add_f32_e32 v17, v17, v223
	v_add_f32_e32 v16, v16, v224
	v_add_f32_e32 v17, v17, v225
	v_cvt_pk_bf16_f32 v218, v218, v219
	v_cvt_pk_bf16_f32 v219, v220, v221
	v_cvt_pk_bf16_f32 v220, v222, v223
	v_cvt_pk_bf16_f32 v221, v224, v225
	v_cvt_pk_bf16_f32 v222, v226, v227
	v_cvt_pk_bf16_f32 v223, v228, v229
	v_cvt_pk_bf16_f32 v224, v230, v231
	v_cvt_pk_bf16_f32 v225, v232, v233
	s_waitcnt lgkmcnt(0)
	v_mfma_f32_32x32x16_bf16 v[20:35], v[234:237], v[218:221], v[20:35]
	v_exp_f32_e32 v118, v118
	v_exp_f32_e32 v119, v119
	v_exp_f32_e32 v120, v120
	v_mfma_f32_32x32x16_bf16 v[36:51], v[248:251], v[218:221], v[36:51]
	v_exp_f32_e32 v121, v121
	v_exp_f32_e32 v122, v122
	v_exp_f32_e32 v123, v123
	v_mfma_f32_32x32x16_bf16 v[20:35], v[244:247], v[222:225], v[20:35]
	v_exp_f32_e32 v124, v124
	v_exp_f32_e32 v125, v125
	v_exp_f32_e32 v126, v126
	v_mfma_f32_32x32x16_bf16 v[36:51], v[252:255], v[222:225], v[36:51]
	v_exp_f32_e32 v127, v127
	v_exp_f32_e32 v128, v128
	v_exp_f32_e32 v129, v129
	v_exp_f32_e32 v130, v130
	v_exp_f32_e32 v131, v131
	v_exp_f32_e32 v132, v132
	v_exp_f32_e32 v133, v133
	v_add_f32_e32 v238, v238, v118
	v_add_f32_e32 v239, v239, v119
	v_add_f32_e32 v238, v238, v120
	v_add_f32_e32 v239, v239, v121
	v_add_f32_e32 v238, v238, v122
	v_add_f32_e32 v239, v239, v123
	v_add_f32_e32 v238, v238, v124
	v_add_f32_e32 v239, v239, v125
	v_cvt_pk_bf16_f32 v118, v118, v119
	v_cvt_pk_bf16_f32 v119, v120, v121
	v_cvt_pk_bf16_f32 v120, v122, v123
	v_cvt_pk_bf16_f32 v121, v124, v125
	v_cvt_pk_bf16_f32 v122, v126, v127
	v_cvt_pk_bf16_f32 v123, v128, v129
	v_cvt_pk_bf16_f32 v124, v130, v131
	v_cvt_pk_bf16_f32 v125, v132, v133
	v_mfma_f32_32x32x16_bf16 v[68:83], v[234:237], v[118:121], v[68:83]
	v_add_f32_e32 v16, v16, v226
	v_add_f32_e32 v17, v17, v227
	v_add_f32_e32 v16, v16, v228
	v_add_f32_e32 v17, v17, v229
	v_mfma_f32_32x32x16_bf16 v[52:67], v[248:251], v[118:121], v[52:67]
	v_add_f32_e32 v16, v16, v230
	v_add_f32_e32 v17, v17, v231
	v_add_f32_e32 v16, v16, v232
	v_add_f32_e32 v17, v17, v233
	v_mfma_f32_32x32x16_bf16 v[68:83], v[244:247], v[122:125], v[68:83]
	v_add_f32_e32 v238, v238, v126
	v_add_f32_e32 v239, v239, v127
	v_add_f32_e32 v238, v238, v128
	v_add_f32_e32 v239, v239, v129
	v_mfma_f32_32x32x16_bf16 v[52:67], v[252:255], v[122:125], v[52:67]
	v_add_f32_e32 v238, v238, v130
	v_add_f32_e32 v239, v239, v131
	v_add_f32_e32 v238, v238, v132
	v_add_f32_e32 v239, v239, v133
	s_setprio 0
	v_add_f32_e32 v16, v16, v17
	v_add_f32_e32 v238, v238, v239
	v_add_f32_e32 v180, v180, v16
	v_add_f32_e32 v181, v181, v238
	s_branch .LBB0_653
.Lflt_v0:
	ds_read_b128 v[4:7], v198
	ds_read_b128 v[8:11], v206
	ds_read_b128 v[12:15], v207
	ds_read_b128 v[214:217], v208
	ds_read_b128 v[234:237], v198 offset:4096
	ds_read_b128 v[244:247], v206 offset:4096
	ds_read_b128 v[248:251], v207 offset:4096
	ds_read_b128 v[252:255], v208 offset:4096
	s_setprio 1
	s_waitcnt lgkmcnt(7)
	v_mfma_f32_32x32x16_bf16 v[118:133], v[4:7], v[134:137], v[86:101]
	s_waitcnt lgkmcnt(6)
	v_mfma_f32_32x32x16_bf16 v[118:133], v[8:11], v[138:141], v[118:133]
	s_waitcnt lgkmcnt(5)
	v_mfma_f32_32x32x16_bf16 v[118:133], v[12:15], v[142:145], v[118:133]
	s_waitcnt lgkmcnt(4)
	v_mfma_f32_32x32x16_bf16 v[118:133], v[214:217], v[150:153], v[118:133]
	v_mfma_f32_32x32x16_bf16 v[102:117], v[4:7], v[146:149], v[86:101]
	ds_read_b64_tr_b16 v[4:5], v200 offset:8192
	ds_read_b64_tr_b16 v[6:7], v200 offset:9216
	v_mfma_f32_32x32x16_bf16 v[102:117], v[8:11], v[154:157], v[102:117]
	ds_read_b64_tr_b16 v[8:9], v200 offset:10240
	ds_read_b64_tr_b16 v[10:11], v200 offset:11264
	s_nop 5
	v_exp_f32_e32 v118, v118
	v_exp_f32_e32 v119, v119
	v_exp_f32_e32 v120, v120
	v_mfma_f32_32x32x16_bf16 v[102:117], v[12:15], v[158:161], v[102:117]
	ds_read_b64_tr_b16 v[12:13], v201 offset:8192
	ds_read_b64_tr_b16 v[14:15], v201 offset:9216
	v_exp_f32_e32 v121, v121
	v_exp_f32_e32 v122, v122
	v_exp_f32_e32 v123, v123
	v_mfma_f32_32x32x16_bf16 v[102:117], v[214:217], v[162:165], v[102:117]
	ds_read_b64_tr_b16 v[214:215], v201 offset:10240
	ds_read_b64_tr_b16 v[216:217], v201 offset:11264
	v_exp_f32_e32 v124, v124
	v_exp_f32_e32 v125, v125
	v_exp_f32_e32 v126, v126
	s_waitcnt lgkmcnt(8)
	v_mfma_f32_32x32x16_bf16 v[218:233], v[234:237], v[134:137], v[86:101]
	v_exp_f32_e32 v127, v127
	v_exp_f32_e32 v128, v128
	v_exp_f32_e32 v129, v129
	v_mfma_f32_32x32x16_bf16 v[218:233], v[244:247], v[138:141], v[218:233]
	v_exp_f32_e32 v130, v130
	v_exp_f32_e32 v131, v131
	v_exp_f32_e32 v132, v132
	v_mfma_f32_32x32x16_bf16 v[218:233], v[248:251], v[142:145], v[218:233]
	v_exp_f32_e32 v133, v133
	v_add_f32_e32 v16, v118, v120
	v_add_f32_e32 v17, v119, v121
	v_add_f32_e32 v16, v16, v122
	v_add_f32_e32 v17, v17, v123
	v_add_f32_e32 v16, v16, v124
	v_add_f32_e32 v17, v17, v125
	v_cvt_pk_bf16_f32 v118, v118, v119
	v_cvt_pk_bf16_f32 v119, v120, v121
	v_cvt_pk_bf16_f32 v120, v122, v123
	v_mfma_f32_32x32x16_bf16 v[218:233], v[252:255], v[150:153], v[218:233]
	v_cvt_pk_bf16_f32 v121, v124, v125
	v_cvt_pk_bf16_f32 v122, v126, v127
	v_cvt_pk_bf16_f32 v123, v128, v129
	v_cvt_pk_bf16_f32 v124, v130, v131
	v_cvt_pk_bf16_f32 v125, v132, v133
	v_add_f32_e32 v16, v16, v126
	v_add_f32_e32 v17, v17, v127
	v_add_f32_e32 v16, v16, v128
	v_add_f32_e32 v17, v17, v129
	v_add_f32_e32 v16, v16, v130
	v_add_f32_e32 v17, v17, v131
	v_add_f32_e32 v16, v16, v132
	v_add_f32_e32 v17, v17, v133
	s_waitcnt lgkmcnt(0)
	v_mfma_f32_32x32x16_bf16 v[20:35], v[4:7], v[118:121], v[20:35]
	v_exp_f32_e32 v102, v102
	v_exp_f32_e32 v103, v103
	v_exp_f32_e32 v104, v104
	v_mfma_f32_32x32x16_bf16 v[36:51], v[12:15], v[118:121], v[36:51]
	v_exp_f32_e32 v105, v105
	v_exp_f32_e32 v106, v106
	v_exp_f32_e32 v107, v107
	v_mfma_f32_32x32x16_bf16 v[20:35], v[8:11], v[122:125], v[20:35]
	v_exp_f32_e32 v108, v108
	v_exp_f32_e32 v109, v109
	v_exp_f32_e32 v110, v110
	v_mfma_f32_32x32x16_bf16 v[36:51], v[214:217], v[122:125], v[36:51]
	v_exp_f32_e32 v111, v111
	v_exp_f32_e32 v112, v112
	v_exp_f32_e32 v113, v113
	v_mfma_f32_32x32x16_bf16 v[118:133], v[234:237], v[146:149], v[86:101]
	ds_read_b64_tr_b16 v[234:235], v200 offset:12288
	ds_read_b64_tr_b16 v[236:237], v200 offset:13312
	v_exp_f32_e32 v114, v114
	v_exp_f32_e32 v115, v115
	v_exp_f32_e32 v116, v116
	v_mfma_f32_32x32x16_bf16 v[118:133], v[244:247], v[154:157], v[118:133]
	ds_read_b64_tr_b16 v[244:245], v200 offset:14336
	ds_read_b64_tr_b16 v[246:247], v200 offset:15360
	v_exp_f32_e32 v117, v117
	v_add_f32_e32 v238, v102, v104
	v_add_f32_e32 v239, v103, v105
	v_add_f32_e32 v238, v238, v106
	v_add_f32_e32 v239, v239, v107
	v_add_f32_e32 v238, v238, v108
	v_add_f32_e32 v239, v239, v109
	v_cvt_pk_bf16_f32 v102, v102, v103
	v_cvt_pk_bf16_f32 v103, v104, v105
	v_mfma_f32_32x32x16_bf16 v[118:133], v[248:251], v[158:161], v[118:133]
	ds_read_b64_tr_b16 v[248:249], v201 offset:12288
	ds_read_b64_tr_b16 v[250:251], v201 offset:13312
	v_cvt_pk_bf16_f32 v104, v106, v107
	v_cvt_pk_bf16_f32 v105, v108, v109
	v_cvt_pk_bf16_f32 v106, v110, v111
	v_cvt_pk_bf16_f32 v107, v112, v113
	v_cvt_pk_bf16_f32 v108, v114, v115
	v_cvt_pk_bf16_f32 v109, v116, v117
	v_mfma_f32_32x32x16_bf16 v[118:133], v[252:255], v[162:165], v[118:133]
	ds_read_b64_tr_b16 v[252:253], v201 offset:14336
	ds_read_b64_tr_b16 v[254:255], v201 offset:15360
	v_add_f32_e32 v238, v238, v110
	v_add_f32_e32 v239, v239, v111
	v_add_f32_e32 v238, v238, v112
	v_add_f32_e32 v239, v239, v113
	v_add_f32_e32 v238, v238, v114
	v_add_f32_e32 v239, v239, v115
	v_add_f32_e32 v238, v238, v116
	v_add_f32_e32 v239, v239, v117
	v_mfma_f32_32x32x16_bf16 v[68:83], v[4:7], v[102:105], v[68:83]
	v_exp_f32_e32 v218, v218
	v_exp_f32_e32 v219, v219
	v_exp_f32_e32 v220, v220
	v_mfma_f32_32x32x16_bf16 v[52:67], v[12:15], v[102:105], v[52:67]
	v_exp_f32_e32 v221, v221
	v_exp_f32_e32 v222, v222
	v_exp_f32_e32 v223, v223
	v_mfma_f32_32x32x16_bf16 v[68:83], v[8:11], v[106:109], v[68:83]
	v_exp_f32_e32 v224, v224
	v_exp_f32_e32 v225, v225
	v_exp_f32_e32 v226, v226
	v_mfma_f32_32x32x16_bf16 v[52:67], v[214:217], v[106:109], v[52:67]
	v_exp_f32_e32 v227, v227
	v_exp_f32_e32 v228, v228
	v_exp_f32_e32 v229, v229
	v_exp_f32_e32 v230, v230
	v_exp_f32_e32 v231, v231
	v_exp_f32_e32 v232, v232
	v_exp_f32_e32 v233, v233
	v_add_f32_e32 v16, v16, v218
	v_add_f32_e32 v17, v17, v219
	v_add_f32_e32 v16, v16, v220
	v_add_f32_e32 v17, v17, v221
	v_add_f32_e32 v16, v16, v222
	v_add_f32_e32 v17, v17, v223
	v_add_f32_e32 v16, v16, v224
	v_add_f32_e32 v17, v17, v225
	v_cvt_pk_bf16_f32 v218, v218, v219
	v_cvt_pk_bf16_f32 v219, v220, v221
	v_cvt_pk_bf16_f32 v220, v222, v223
	v_cvt_pk_bf16_f32 v221, v224, v225
	v_cvt_pk_bf16_f32 v222, v226, v227
	v_cvt_pk_bf16_f32 v223, v228, v229
	v_cvt_pk_bf16_f32 v224, v230, v231
	v_cvt_pk_bf16_f32 v225, v232, v233
	s_waitcnt lgkmcnt(0)
	v_mfma_f32_32x32x16_bf16 v[20:35], v[234:237], v[218:221], v[20:35]
	v_exp_f32_e32 v118, v118
	v_exp_f32_e32 v119, v119
	v_exp_f32_e32 v120, v120
	v_mfma_f32_32x32x16_bf16 v[36:51], v[248:251], v[218:221], v[36:51]
	v_exp_f32_e32 v121, v121
	v_exp_f32_e32 v122, v122
	v_exp_f32_e32 v123, v123
	v_mfma_f32_32x32x16_bf16 v[20:35], v[244:247], v[222:225], v[20:35]
	v_exp_f32_e32 v124, v124
	v_exp_f32_e32 v125, v125
	v_exp_f32_e32 v126, v126
	v_mfma_f32_32x32x16_bf16 v[36:51], v[252:255], v[222:225], v[36:51]
	v_exp_f32_e32 v127, v127
	v_exp_f32_e32 v128, v128
	v_exp_f32_e32 v129, v129
	v_exp_f32_e32 v130, v130
	v_exp_f32_e32 v131, v131
	v_exp_f32_e32 v132, v132
	v_exp_f32_e32 v133, v133
	v_add_f32_e32 v238, v238, v118
	v_add_f32_e32 v239, v239, v119
	v_add_f32_e32 v238, v238, v120
	v_add_f32_e32 v239, v239, v121
	v_add_f32_e32 v238, v238, v122
	v_add_f32_e32 v239, v239, v123
	v_add_f32_e32 v238, v238, v124
	v_add_f32_e32 v239, v239, v125
	v_cvt_pk_bf16_f32 v118, v118, v119
	v_cvt_pk_bf16_f32 v119, v120, v121
	v_cvt_pk_bf16_f32 v120, v122, v123
	v_cvt_pk_bf16_f32 v121, v124, v125
	v_cvt_pk_bf16_f32 v122, v126, v127
	v_cvt_pk_bf16_f32 v123, v128, v129
	v_cvt_pk_bf16_f32 v124, v130, v131
	v_cvt_pk_bf16_f32 v125, v132, v133
	v_mfma_f32_32x32x16_bf16 v[68:83], v[234:237], v[118:121], v[68:83]
	v_add_f32_e32 v16, v16, v226
	v_add_f32_e32 v17, v17, v227
	v_add_f32_e32 v16, v16, v228
	v_add_f32_e32 v17, v17, v229
	v_mfma_f32_32x32x16_bf16 v[52:67], v[248:251], v[118:121], v[52:67]
	v_add_f32_e32 v16, v16, v230
	v_add_f32_e32 v17, v17, v231
	v_add_f32_e32 v16, v16, v232
	v_add_f32_e32 v17, v17, v233
	v_mfma_f32_32x32x16_bf16 v[68:83], v[244:247], v[122:125], v[68:83]
	v_add_f32_e32 v238, v238, v126
	v_add_f32_e32 v239, v239, v127
	v_add_f32_e32 v238, v238, v128
	v_add_f32_e32 v239, v239, v129
	v_mfma_f32_32x32x16_bf16 v[52:67], v[252:255], v[122:125], v[52:67]
	v_add_f32_e32 v238, v238, v130
	v_add_f32_e32 v239, v239, v131
	v_add_f32_e32 v238, v238, v132
	v_add_f32_e32 v239, v239, v133
	s_setprio 0
	v_add_f32_e32 v16, v16, v17
	v_add_f32_e32 v238, v238, v239
	v_add_f32_e32 v180, v180, v16
	v_add_f32_e32 v181, v181, v238
	s_branch .LBB0_653
.Lflt_v1:
	ds_read_b128 v[4:7], v198 offset:16384
	ds_read_b128 v[8:11], v206 offset:16384
	ds_read_b128 v[12:15], v207 offset:16384
	ds_read_b128 v[214:217], v208 offset:16384
	ds_read_b128 v[234:237], v198 offset:20480
	ds_read_b128 v[244:247], v206 offset:20480
	ds_read_b128 v[248:251], v207 offset:20480
	ds_read_b128 v[252:255], v208 offset:20480
	s_setprio 1
	s_waitcnt lgkmcnt(7)
	v_mfma_f32_32x32x16_bf16 v[118:133], v[4:7], v[134:137], v[86:101]
	s_waitcnt lgkmcnt(6)
	v_mfma_f32_32x32x16_bf16 v[118:133], v[8:11], v[138:141], v[118:133]
	s_waitcnt lgkmcnt(5)
	v_mfma_f32_32x32x16_bf16 v[118:133], v[12:15], v[142:145], v[118:133]
	s_waitcnt lgkmcnt(4)
	v_mfma_f32_32x32x16_bf16 v[118:133], v[214:217], v[150:153], v[118:133]
	v_mfma_f32_32x32x16_bf16 v[102:117], v[4:7], v[146:149], v[86:101]
	ds_read_b64_tr_b16 v[4:5], v200 offset:24576
	ds_read_b64_tr_b16 v[6:7], v200 offset:25600
	v_mfma_f32_32x32x16_bf16 v[102:117], v[8:11], v[154:157], v[102:117]
	ds_read_b64_tr_b16 v[8:9], v200 offset:26624
	ds_read_b64_tr_b16 v[10:11], v200 offset:27648
	s_nop 5
	v_exp_f32_e32 v118, v118
	v_exp_f32_e32 v119, v119
	v_exp_f32_e32 v120, v120
	v_mfma_f32_32x32x16_bf16 v[102:117], v[12:15], v[158:161], v[102:117]
	ds_read_b64_tr_b16 v[12:13], v201 offset:24576
	ds_read_b64_tr_b16 v[14:15], v201 offset:25600
	v_exp_f32_e32 v121, v121
	v_exp_f32_e32 v122, v122
	v_exp_f32_e32 v123, v123
	v_mfma_f32_32x32x16_bf16 v[102:117], v[214:217], v[162:165], v[102:117]
	ds_read_b64_tr_b16 v[214:215], v201 offset:26624
	ds_read_b64_tr_b16 v[216:217], v201 offset:27648
	v_exp_f32_e32 v124, v124
	v_exp_f32_e32 v125, v125
	v_exp_f32_e32 v126, v126
	s_waitcnt lgkmcnt(8)
	v_mfma_f32_32x32x16_bf16 v[218:233], v[234:237], v[134:137], v[86:101]
	v_exp_f32_e32 v127, v127
	v_exp_f32_e32 v128, v128
	v_exp_f32_e32 v129, v129
	v_mfma_f32_32x32x16_bf16 v[218:233], v[244:247], v[138:141], v[218:233]
	v_exp_f32_e32 v130, v130
	v_exp_f32_e32 v131, v131
	v_exp_f32_e32 v132, v132
	v_mfma_f32_32x32x16_bf16 v[218:233], v[248:251], v[142:145], v[218:233]
	v_exp_f32_e32 v133, v133
	v_add_f32_e32 v16, v118, v120
	v_add_f32_e32 v17, v119, v121
	v_add_f32_e32 v16, v16, v122
	v_add_f32_e32 v17, v17, v123
	v_add_f32_e32 v16, v16, v124
	v_add_f32_e32 v17, v17, v125
	v_cvt_pk_bf16_f32 v118, v118, v119
	v_cvt_pk_bf16_f32 v119, v120, v121
	v_cvt_pk_bf16_f32 v120, v122, v123
	v_mfma_f32_32x32x16_bf16 v[218:233], v[252:255], v[150:153], v[218:233]
	v_cvt_pk_bf16_f32 v121, v124, v125
	v_cvt_pk_bf16_f32 v122, v126, v127
	v_cvt_pk_bf16_f32 v123, v128, v129
	v_cvt_pk_bf16_f32 v124, v130, v131
	v_cvt_pk_bf16_f32 v125, v132, v133
	v_add_f32_e32 v16, v16, v126
	v_add_f32_e32 v17, v17, v127
	v_add_f32_e32 v16, v16, v128
	v_add_f32_e32 v17, v17, v129
	v_add_f32_e32 v16, v16, v130
	v_add_f32_e32 v17, v17, v131
	v_add_f32_e32 v16, v16, v132
	v_add_f32_e32 v17, v17, v133
	s_waitcnt lgkmcnt(0)
	v_mfma_f32_32x32x16_bf16 v[20:35], v[4:7], v[118:121], v[20:35]
	v_exp_f32_e32 v102, v102
	v_exp_f32_e32 v103, v103
	v_exp_f32_e32 v104, v104
	v_mfma_f32_32x32x16_bf16 v[36:51], v[12:15], v[118:121], v[36:51]
	v_exp_f32_e32 v105, v105
	v_exp_f32_e32 v106, v106
	v_exp_f32_e32 v107, v107
	v_mfma_f32_32x32x16_bf16 v[20:35], v[8:11], v[122:125], v[20:35]
	v_exp_f32_e32 v108, v108
	v_exp_f32_e32 v109, v109
	v_exp_f32_e32 v110, v110
	v_mfma_f32_32x32x16_bf16 v[36:51], v[214:217], v[122:125], v[36:51]
	v_exp_f32_e32 v111, v111
	v_exp_f32_e32 v112, v112
	v_exp_f32_e32 v113, v113
	v_mfma_f32_32x32x16_bf16 v[118:133], v[234:237], v[146:149], v[86:101]
	ds_read_b64_tr_b16 v[234:235], v200 offset:28672
	ds_read_b64_tr_b16 v[236:237], v200 offset:29696
	v_exp_f32_e32 v114, v114
	v_exp_f32_e32 v115, v115
	v_exp_f32_e32 v116, v116
	v_mfma_f32_32x32x16_bf16 v[118:133], v[244:247], v[154:157], v[118:133]
	ds_read_b64_tr_b16 v[244:245], v200 offset:30720
	ds_read_b64_tr_b16 v[246:247], v200 offset:31744
	v_exp_f32_e32 v117, v117
	v_add_f32_e32 v238, v102, v104
	v_add_f32_e32 v239, v103, v105
	v_add_f32_e32 v238, v238, v106
	v_add_f32_e32 v239, v239, v107
	v_add_f32_e32 v238, v238, v108
	v_add_f32_e32 v239, v239, v109
	v_cvt_pk_bf16_f32 v102, v102, v103
	v_cvt_pk_bf16_f32 v103, v104, v105
	v_mfma_f32_32x32x16_bf16 v[118:133], v[248:251], v[158:161], v[118:133]
	ds_read_b64_tr_b16 v[248:249], v201 offset:28672
	ds_read_b64_tr_b16 v[250:251], v201 offset:29696
	v_cvt_pk_bf16_f32 v104, v106, v107
	v_cvt_pk_bf16_f32 v105, v108, v109
	v_cvt_pk_bf16_f32 v106, v110, v111
	v_cvt_pk_bf16_f32 v107, v112, v113
	v_cvt_pk_bf16_f32 v108, v114, v115
	v_cvt_pk_bf16_f32 v109, v116, v117
	v_mfma_f32_32x32x16_bf16 v[118:133], v[252:255], v[162:165], v[118:133]
	ds_read_b64_tr_b16 v[252:253], v201 offset:30720
	ds_read_b64_tr_b16 v[254:255], v201 offset:31744
	v_add_f32_e32 v238, v238, v110
	v_add_f32_e32 v239, v239, v111
	v_add_f32_e32 v238, v238, v112
	v_add_f32_e32 v239, v239, v113
	v_add_f32_e32 v238, v238, v114
	v_add_f32_e32 v239, v239, v115
	v_add_f32_e32 v238, v238, v116
	v_add_f32_e32 v239, v239, v117
	v_mfma_f32_32x32x16_bf16 v[68:83], v[4:7], v[102:105], v[68:83]
	v_exp_f32_e32 v218, v218
	v_exp_f32_e32 v219, v219
	v_exp_f32_e32 v220, v220
	v_mfma_f32_32x32x16_bf16 v[52:67], v[12:15], v[102:105], v[52:67]
	v_exp_f32_e32 v221, v221
	v_exp_f32_e32 v222, v222
	v_exp_f32_e32 v223, v223
	v_mfma_f32_32x32x16_bf16 v[68:83], v[8:11], v[106:109], v[68:83]
	v_exp_f32_e32 v224, v224
	v_exp_f32_e32 v225, v225
	v_exp_f32_e32 v226, v226
	v_mfma_f32_32x32x16_bf16 v[52:67], v[214:217], v[106:109], v[52:67]
	v_exp_f32_e32 v227, v227
	v_exp_f32_e32 v228, v228
	v_exp_f32_e32 v229, v229
	v_exp_f32_e32 v230, v230
	v_exp_f32_e32 v231, v231
	v_exp_f32_e32 v232, v232
	v_exp_f32_e32 v233, v233
	v_add_f32_e32 v16, v16, v218
	v_add_f32_e32 v17, v17, v219
	v_add_f32_e32 v16, v16, v220
	v_add_f32_e32 v17, v17, v221
	v_add_f32_e32 v16, v16, v222
	v_add_f32_e32 v17, v17, v223
	v_add_f32_e32 v16, v16, v224
	v_add_f32_e32 v17, v17, v225
	v_cvt_pk_bf16_f32 v218, v218, v219
	v_cvt_pk_bf16_f32 v219, v220, v221
	v_cvt_pk_bf16_f32 v220, v222, v223
	v_cvt_pk_bf16_f32 v221, v224, v225
	v_cvt_pk_bf16_f32 v222, v226, v227
	v_cvt_pk_bf16_f32 v223, v228, v229
	v_cvt_pk_bf16_f32 v224, v230, v231
	v_cvt_pk_bf16_f32 v225, v232, v233
	s_waitcnt lgkmcnt(0)
	v_mfma_f32_32x32x16_bf16 v[20:35], v[234:237], v[218:221], v[20:35]
	v_exp_f32_e32 v118, v118
	v_exp_f32_e32 v119, v119
	v_exp_f32_e32 v120, v120
	v_mfma_f32_32x32x16_bf16 v[36:51], v[248:251], v[218:221], v[36:51]
	v_exp_f32_e32 v121, v121
	v_exp_f32_e32 v122, v122
	v_exp_f32_e32 v123, v123
	v_mfma_f32_32x32x16_bf16 v[20:35], v[244:247], v[222:225], v[20:35]
	v_exp_f32_e32 v124, v124
	v_exp_f32_e32 v125, v125
	v_exp_f32_e32 v126, v126
	v_mfma_f32_32x32x16_bf16 v[36:51], v[252:255], v[222:225], v[36:51]
	v_exp_f32_e32 v127, v127
	v_exp_f32_e32 v128, v128
	v_exp_f32_e32 v129, v129
	v_exp_f32_e32 v130, v130
	v_exp_f32_e32 v131, v131
	v_exp_f32_e32 v132, v132
	v_exp_f32_e32 v133, v133
	v_add_f32_e32 v238, v238, v118
	v_add_f32_e32 v239, v239, v119
	v_add_f32_e32 v238, v238, v120
	v_add_f32_e32 v239, v239, v121
	v_add_f32_e32 v238, v238, v122
	v_add_f32_e32 v239, v239, v123
	v_add_f32_e32 v238, v238, v124
	v_add_f32_e32 v239, v239, v125
	v_cvt_pk_bf16_f32 v118, v118, v119
	v_cvt_pk_bf16_f32 v119, v120, v121
	v_cvt_pk_bf16_f32 v120, v122, v123
	v_cvt_pk_bf16_f32 v121, v124, v125
	v_cvt_pk_bf16_f32 v122, v126, v127
	v_cvt_pk_bf16_f32 v123, v128, v129
	v_cvt_pk_bf16_f32 v124, v130, v131
	v_cvt_pk_bf16_f32 v125, v132, v133
	v_mfma_f32_32x32x16_bf16 v[68:83], v[234:237], v[118:121], v[68:83]
	v_add_f32_e32 v16, v16, v226
	v_add_f32_e32 v17, v17, v227
	v_add_f32_e32 v16, v16, v228
	v_add_f32_e32 v17, v17, v229
	v_mfma_f32_32x32x16_bf16 v[52:67], v[248:251], v[118:121], v[52:67]
	v_add_f32_e32 v16, v16, v230
	v_add_f32_e32 v17, v17, v231
	v_add_f32_e32 v16, v16, v232
	v_add_f32_e32 v17, v17, v233
	v_mfma_f32_32x32x16_bf16 v[68:83], v[244:247], v[122:125], v[68:83]
	v_add_f32_e32 v238, v238, v126
	v_add_f32_e32 v239, v239, v127
	v_add_f32_e32 v238, v238, v128
	v_add_f32_e32 v239, v239, v129
	v_mfma_f32_32x32x16_bf16 v[52:67], v[252:255], v[122:125], v[52:67]
	v_add_f32_e32 v238, v238, v130
	v_add_f32_e32 v239, v239, v131
	v_add_f32_e32 v238, v238, v132
	v_add_f32_e32 v239, v239, v133
	s_setprio 0
	v_add_f32_e32 v16, v16, v17
	v_add_f32_e32 v238, v238, v239
	v_add_f32_e32 v180, v180, v16
	v_add_f32_e32 v181, v181, v238
	s_branch .LBB0_653
.Lflt_v2:
	ds_read_b128 v[4:7], v198 offset:32768
	ds_read_b128 v[8:11], v206 offset:32768
	ds_read_b128 v[12:15], v207 offset:32768
	ds_read_b128 v[214:217], v208 offset:32768
	ds_read_b128 v[234:237], v198 offset:36864
	ds_read_b128 v[244:247], v206 offset:36864
	ds_read_b128 v[248:251], v207 offset:36864
	ds_read_b128 v[252:255], v208 offset:36864
	s_setprio 1
	s_waitcnt lgkmcnt(7)
	v_mfma_f32_32x32x16_bf16 v[118:133], v[4:7], v[134:137], v[86:101]
	s_waitcnt lgkmcnt(6)
	v_mfma_f32_32x32x16_bf16 v[118:133], v[8:11], v[138:141], v[118:133]
	s_waitcnt lgkmcnt(5)
	v_mfma_f32_32x32x16_bf16 v[118:133], v[12:15], v[142:145], v[118:133]
	s_waitcnt lgkmcnt(4)
	v_mfma_f32_32x32x16_bf16 v[118:133], v[214:217], v[150:153], v[118:133]
	v_mfma_f32_32x32x16_bf16 v[102:117], v[4:7], v[146:149], v[86:101]
	ds_read_b64_tr_b16 v[4:5], v200 offset:40960
	ds_read_b64_tr_b16 v[6:7], v200 offset:41984
	v_mfma_f32_32x32x16_bf16 v[102:117], v[8:11], v[154:157], v[102:117]
	ds_read_b64_tr_b16 v[8:9], v200 offset:43008
	ds_read_b64_tr_b16 v[10:11], v200 offset:44032
	s_nop 5
	v_exp_f32_e32 v118, v118
	v_exp_f32_e32 v119, v119
	v_exp_f32_e32 v120, v120
	v_mfma_f32_32x32x16_bf16 v[102:117], v[12:15], v[158:161], v[102:117]
	ds_read_b64_tr_b16 v[12:13], v201 offset:40960
	ds_read_b64_tr_b16 v[14:15], v201 offset:41984
	v_exp_f32_e32 v121, v121
	v_exp_f32_e32 v122, v122
	v_exp_f32_e32 v123, v123
	v_mfma_f32_32x32x16_bf16 v[102:117], v[214:217], v[162:165], v[102:117]
	ds_read_b64_tr_b16 v[214:215], v201 offset:43008
	ds_read_b64_tr_b16 v[216:217], v201 offset:44032
	v_exp_f32_e32 v124, v124
	v_exp_f32_e32 v125, v125
	v_exp_f32_e32 v126, v126
	s_waitcnt lgkmcnt(8)
	v_mfma_f32_32x32x16_bf16 v[218:233], v[234:237], v[134:137], v[86:101]
	v_exp_f32_e32 v127, v127
	v_exp_f32_e32 v128, v128
	v_exp_f32_e32 v129, v129
	v_mfma_f32_32x32x16_bf16 v[218:233], v[244:247], v[138:141], v[218:233]
	v_exp_f32_e32 v130, v130
	v_exp_f32_e32 v131, v131
	v_exp_f32_e32 v132, v132
	v_mfma_f32_32x32x16_bf16 v[218:233], v[248:251], v[142:145], v[218:233]
	v_exp_f32_e32 v133, v133
	v_add_f32_e32 v16, v118, v120
	v_add_f32_e32 v17, v119, v121
	v_add_f32_e32 v16, v16, v122
	v_add_f32_e32 v17, v17, v123
	v_add_f32_e32 v16, v16, v124
	v_add_f32_e32 v17, v17, v125
	v_cvt_pk_bf16_f32 v118, v118, v119
	v_cvt_pk_bf16_f32 v119, v120, v121
	v_cvt_pk_bf16_f32 v120, v122, v123
	v_mfma_f32_32x32x16_bf16 v[218:233], v[252:255], v[150:153], v[218:233]
	v_cvt_pk_bf16_f32 v121, v124, v125
	v_cvt_pk_bf16_f32 v122, v126, v127
	v_cvt_pk_bf16_f32 v123, v128, v129
	v_cvt_pk_bf16_f32 v124, v130, v131
	v_cvt_pk_bf16_f32 v125, v132, v133
	v_add_f32_e32 v16, v16, v126
	v_add_f32_e32 v17, v17, v127
	v_add_f32_e32 v16, v16, v128
	v_add_f32_e32 v17, v17, v129
	v_add_f32_e32 v16, v16, v130
	v_add_f32_e32 v17, v17, v131
	v_add_f32_e32 v16, v16, v132
	v_add_f32_e32 v17, v17, v133
	s_waitcnt lgkmcnt(0)
	v_mfma_f32_32x32x16_bf16 v[20:35], v[4:7], v[118:121], v[20:35]
	v_exp_f32_e32 v102, v102
	v_exp_f32_e32 v103, v103
	v_exp_f32_e32 v104, v104
	v_mfma_f32_32x32x16_bf16 v[36:51], v[12:15], v[118:121], v[36:51]
	v_exp_f32_e32 v105, v105
	v_exp_f32_e32 v106, v106
	v_exp_f32_e32 v107, v107
	v_mfma_f32_32x32x16_bf16 v[20:35], v[8:11], v[122:125], v[20:35]
	v_exp_f32_e32 v108, v108
	v_exp_f32_e32 v109, v109
	v_exp_f32_e32 v110, v110
	v_mfma_f32_32x32x16_bf16 v[36:51], v[214:217], v[122:125], v[36:51]
	v_exp_f32_e32 v111, v111
	v_exp_f32_e32 v112, v112
	v_exp_f32_e32 v113, v113
	v_mfma_f32_32x32x16_bf16 v[118:133], v[234:237], v[146:149], v[86:101]
	ds_read_b64_tr_b16 v[234:235], v200 offset:45056
	ds_read_b64_tr_b16 v[236:237], v200 offset:46080
	v_exp_f32_e32 v114, v114
	v_exp_f32_e32 v115, v115
	v_exp_f32_e32 v116, v116
	v_mfma_f32_32x32x16_bf16 v[118:133], v[244:247], v[154:157], v[118:133]
	ds_read_b64_tr_b16 v[244:245], v200 offset:47104
	ds_read_b64_tr_b16 v[246:247], v200 offset:48128
	v_exp_f32_e32 v117, v117
	v_add_f32_e32 v238, v102, v104
	v_add_f32_e32 v239, v103, v105
	v_add_f32_e32 v238, v238, v106
	v_add_f32_e32 v239, v239, v107
	v_add_f32_e32 v238, v238, v108
	v_add_f32_e32 v239, v239, v109
	v_cvt_pk_bf16_f32 v102, v102, v103
	v_cvt_pk_bf16_f32 v103, v104, v105
	v_mfma_f32_32x32x16_bf16 v[118:133], v[248:251], v[158:161], v[118:133]
	ds_read_b64_tr_b16 v[248:249], v201 offset:45056
	ds_read_b64_tr_b16 v[250:251], v201 offset:46080
	v_cvt_pk_bf16_f32 v104, v106, v107
	v_cvt_pk_bf16_f32 v105, v108, v109
	v_cvt_pk_bf16_f32 v106, v110, v111
	v_cvt_pk_bf16_f32 v107, v112, v113
	v_cvt_pk_bf16_f32 v108, v114, v115
	v_cvt_pk_bf16_f32 v109, v116, v117
	v_mfma_f32_32x32x16_bf16 v[118:133], v[252:255], v[162:165], v[118:133]
	ds_read_b64_tr_b16 v[252:253], v201 offset:47104
	ds_read_b64_tr_b16 v[254:255], v201 offset:48128
	v_add_f32_e32 v238, v238, v110
	v_add_f32_e32 v239, v239, v111
	v_add_f32_e32 v238, v238, v112
	v_add_f32_e32 v239, v239, v113
	v_add_f32_e32 v238, v238, v114
	v_add_f32_e32 v239, v239, v115
	v_add_f32_e32 v238, v238, v116
	v_add_f32_e32 v239, v239, v117
	v_mfma_f32_32x32x16_bf16 v[68:83], v[4:7], v[102:105], v[68:83]
	v_exp_f32_e32 v218, v218
	v_exp_f32_e32 v219, v219
	v_exp_f32_e32 v220, v220
	v_mfma_f32_32x32x16_bf16 v[52:67], v[12:15], v[102:105], v[52:67]
	v_exp_f32_e32 v221, v221
	v_exp_f32_e32 v222, v222
	v_exp_f32_e32 v223, v223
	v_mfma_f32_32x32x16_bf16 v[68:83], v[8:11], v[106:109], v[68:83]
	v_exp_f32_e32 v224, v224
	v_exp_f32_e32 v225, v225
	v_exp_f32_e32 v226, v226
	v_mfma_f32_32x32x16_bf16 v[52:67], v[214:217], v[106:109], v[52:67]
	v_exp_f32_e32 v227, v227
	v_exp_f32_e32 v228, v228
	v_exp_f32_e32 v229, v229
	v_exp_f32_e32 v230, v230
	v_exp_f32_e32 v231, v231
	v_exp_f32_e32 v232, v232
	v_exp_f32_e32 v233, v233
	v_add_f32_e32 v16, v16, v218
	v_add_f32_e32 v17, v17, v219
	v_add_f32_e32 v16, v16, v220
	v_add_f32_e32 v17, v17, v221
	v_add_f32_e32 v16, v16, v222
	v_add_f32_e32 v17, v17, v223
	v_add_f32_e32 v16, v16, v224
	v_add_f32_e32 v17, v17, v225
	v_cvt_pk_bf16_f32 v218, v218, v219
	v_cvt_pk_bf16_f32 v219, v220, v221
	v_cvt_pk_bf16_f32 v220, v222, v223
	v_cvt_pk_bf16_f32 v221, v224, v225
	v_cvt_pk_bf16_f32 v222, v226, v227
	v_cvt_pk_bf16_f32 v223, v228, v229
	v_cvt_pk_bf16_f32 v224, v230, v231
	v_cvt_pk_bf16_f32 v225, v232, v233
	s_waitcnt lgkmcnt(0)
	v_mfma_f32_32x32x16_bf16 v[20:35], v[234:237], v[218:221], v[20:35]
	v_exp_f32_e32 v118, v118
	v_exp_f32_e32 v119, v119
	v_exp_f32_e32 v120, v120
	v_mfma_f32_32x32x16_bf16 v[36:51], v[248:251], v[218:221], v[36:51]
	v_exp_f32_e32 v121, v121
	v_exp_f32_e32 v122, v122
	v_exp_f32_e32 v123, v123
	v_mfma_f32_32x32x16_bf16 v[20:35], v[244:247], v[222:225], v[20:35]
	v_exp_f32_e32 v124, v124
	v_exp_f32_e32 v125, v125
	v_exp_f32_e32 v126, v126
	v_mfma_f32_32x32x16_bf16 v[36:51], v[252:255], v[222:225], v[36:51]
	v_exp_f32_e32 v127, v127
	v_exp_f32_e32 v128, v128
	v_exp_f32_e32 v129, v129
	v_exp_f32_e32 v130, v130
	v_exp_f32_e32 v131, v131
	v_exp_f32_e32 v132, v132
	v_exp_f32_e32 v133, v133
	v_add_f32_e32 v238, v238, v118
	v_add_f32_e32 v239, v239, v119
	v_add_f32_e32 v238, v238, v120
	v_add_f32_e32 v239, v239, v121
	v_add_f32_e32 v238, v238, v122
	v_add_f32_e32 v239, v239, v123
	v_add_f32_e32 v238, v238, v124
	v_add_f32_e32 v239, v239, v125
	v_cvt_pk_bf16_f32 v118, v118, v119
	v_cvt_pk_bf16_f32 v119, v120, v121
	v_cvt_pk_bf16_f32 v120, v122, v123
	v_cvt_pk_bf16_f32 v121, v124, v125
	v_cvt_pk_bf16_f32 v122, v126, v127
	v_cvt_pk_bf16_f32 v123, v128, v129
	v_cvt_pk_bf16_f32 v124, v130, v131
	v_cvt_pk_bf16_f32 v125, v132, v133
	v_mfma_f32_32x32x16_bf16 v[68:83], v[234:237], v[118:121], v[68:83]
	v_add_f32_e32 v16, v16, v226
	v_add_f32_e32 v17, v17, v227
	v_add_f32_e32 v16, v16, v228
	v_add_f32_e32 v17, v17, v229
	v_mfma_f32_32x32x16_bf16 v[52:67], v[248:251], v[118:121], v[52:67]
	v_add_f32_e32 v16, v16, v230
	v_add_f32_e32 v17, v17, v231
	v_add_f32_e32 v16, v16, v232
	v_add_f32_e32 v17, v17, v233
	v_mfma_f32_32x32x16_bf16 v[68:83], v[244:247], v[122:125], v[68:83]
	v_add_f32_e32 v238, v238, v126
	v_add_f32_e32 v239, v239, v127
	v_add_f32_e32 v238, v238, v128
	v_add_f32_e32 v239, v239, v129
	v_mfma_f32_32x32x16_bf16 v[52:67], v[252:255], v[122:125], v[52:67]
	v_add_f32_e32 v238, v238, v130
	v_add_f32_e32 v239, v239, v131
	v_add_f32_e32 v238, v238, v132
	v_add_f32_e32 v239, v239, v133
	s_setprio 0
	v_add_f32_e32 v16, v16, v17
	v_add_f32_e32 v238, v238, v239
	v_add_f32_e32 v180, v180, v16
	v_add_f32_e32 v181, v181, v238
	s_branch .LBB0_653
